# e28: B-loop - wait-state s_nops after m0 writes replaced by useful neighbours (8 instructions fewer per tile), re-aligned
# baseline (speedup 1.0000x reference)
; __device__ __forceinline__ int crow(int r, int hi) { return (r & 3) + 8 * (r >> 2) + 4 * hi; }
; __device__ __forceinline__ int crow(int r, int hi) { return (r & 3) + 8 * (r >> 2) + 4 * hi; }
; #define DMA_K(j_, b_) do { const char* kb_ = (const char*)Kh + (size_t)(j_) * (64 * LD * 2); _Pragma("unroll") for (int i = 0; i < 4; ++i) \
;     __builtin_amdgcn_global_load_lds((const unsigned*)(kb_ + kgo[i]), (LAS unsigned*)(K_las + (b_) * 16384 + (4 * a + i) * 1024), 16, 0, 0); } while (0)
; #define DMA_V(j_, b_) do { const char* vb_ = (const char*)Vh + (size_t)(j_) * (64 * LD * 2); _Pragma("unroll") for (int hf = 0; hf < 2; ++hf) _Pragma("unroll") for (int i = 0; i < 4; ++i) \
;     __builtin_amdgcn_global_load_lds((const unsigned*)(vb_ + hf * 256 + vgo[i]), (LAS unsigned*)(V_las + (b_) * 32768 + hf * 16384 + (4 * a + i) * 1024), 16, 0, 0); } while (0)
; __device__ __forceinline__ void attn_unit2(const bf16* __restrict__ Qb, const bf16* __restrict__ Kh, const bf16* __restrict__ Vh, bf16* __restrict__ Ob,
;                                            int NT, int lim, int qrow0, const float* lut, char* lds, float* scr) {
;     ...
;       if (j + 1 < NT) DMA_K(j + 1, (j + 1) & 1);
;       if (j < NT) DMA_V(j, j & 1);
;       if (j >= 1) {
;         const float* al = al0 + ((j - 1) & 1) * 128;
;         if (__any(al[r32] < 1.f) || __any(al[32 + r32] < 1.f)) {
; #pragma unroll
;           for (int rb = 0; rb < 2; ++rb)
; #pragma unroll
;             for (int d = 0; d < 4; ++d)
; #pragma unroll
;               for (int r = 0; r < 16; ++r) o[rb][d][r] *= al[rb * 32 + crow(r, hi)]; }
.LBB0_432:
	s_and_b32 s14, s7, 0x4000
	s_add_i32 s14, s6, s14
	v_lshl_add_u64 v[156:157], v[148:149], 0, s[36:37]
	s_mov_b32 m0, s14
	v_lshl_add_u64 v[158:159], v[150:151], 0, s[36:37]
	global_load_lds_dwordx4 v[156:157], off
	s_add_i32 m0, s14, 0x400
	v_lshl_add_u64 v[156:157], v[152:153], 0, s[36:37]
	global_load_lds_dwordx4 v[158:159], off
	s_add_i32 m0, s14, 0x800
	v_lshl_add_u64 v[158:159], v[154:155], 0, s[36:37]
	global_load_lds_dwordx4 v[156:157], off
	s_add_i32 m0, s14, 0xc00
	s_nop 0
	global_load_lds_dwordx4 v[158:159], off
.LBB0_433:
	s_and_b32 s14, s10, 1
	s_lshl_b32 s15, s14, 9
	s_add_i32 s15, s4, s15
	v_lshl_add_u32 v177, v172, 2, s15
	ds_read_b32 v200, v177
	s_and_b32 s23, s9, 0x8000
	s_add_i32 s23, s6, s23
	v_lshl_add_u64 v[156:157], v[138:139], 0, s[36:37]
	s_add_i32 m0, s23, 0x8000
	v_lshl_add_u64 v[158:159], v[156:157], 0, s[54:55]
	global_load_lds_dwordx4 v[158:159], off
	s_nop 0
	v_lshl_add_u64 v[158:159], v[142:143], 0, s[36:37]
	v_lshl_add_u64 v[164:165], v[158:159], 0, s[54:55]
	s_add_i32 m0, s23, 0x8400
	v_lshl_add_u64 v[156:157], v[156:157], 0, s[68:69]
	global_load_lds_dwordx4 v[164:165], off
	s_add_i32 m0, s23, 0x8800
	v_lshl_add_u64 v[164:165], v[144:145], 0, s[36:37]
	v_lshl_add_u64 v[178:179], v[164:165], 0, s[54:55]
	global_load_lds_dwordx4 v[178:179], off
	s_add_i32 m0, s23, 0x8c00
	v_lshl_add_u64 v[178:179], v[146:147], 0, s[36:37]
	v_lshl_add_u64 v[180:181], v[178:179], 0, s[54:55]
	global_load_lds_dwordx4 v[180:181], off
	v_lshl_add_u64 v[158:159], v[158:159], 0, s[68:69]
	v_lshl_add_u64 v[164:165], v[164:165], 0, s[68:69]
	v_lshl_add_u64 v[252:253], v[178:179], 0, s[68:69]
	s_waitcnt lgkmcnt(0)
	v_cmp_gt_f32_e32 vcc, 1.0, v200
	s_cmp_lg_u64 vcc, 0
	s_cselect_b64 s[46:47], -1, 0
	s_cbranch_vccz .LBB0_438
	s_andn2_b64 vcc, exec, s[46:47]
	s_cbranch_vccnz .LBB0_436
.LBB0_435:
	v_add_u32_e32 v201, s15, v140
	ds_read_b128 v[178:181], v201
	ds_read_b128 v[182:185], v201 offset:32
	ds_read_b128 v[186:189], v201 offset:64
	ds_read_b128 v[190:193], v201 offset:96
	s_waitcnt lgkmcnt(0)
	v_pk_mul_f32 v[118:119], v[118:119], v[180:181]
	v_pk_mul_f32 v[120:121], v[120:121], v[182:183]
	v_pk_mul_f32 v[124:125], v[124:125], v[186:187]
	v_pk_mul_f32 v[128:129], v[128:129], v[190:191]
	v_pk_mul_f32 v[130:131], v[130:131], v[192:193]
	v_pk_mul_f32 v[126:127], v[126:127], v[188:189]
	v_pk_mul_f32 v[122:123], v[122:123], v[184:185]
	s_nop 0
	v_pk_mul_f32 v[116:117], v[116:117], v[178:179]
	v_pk_mul_f32 v[112:113], v[112:113], v[190:191]
	v_pk_mul_f32 v[108:109], v[108:109], v[186:187]
	v_pk_mul_f32 v[104:105], v[104:105], v[182:183]
	v_pk_mul_f32 v[114:115], v[114:115], v[192:193]
	v_pk_mul_f32 v[110:111], v[110:111], v[188:189]
	v_pk_mul_f32 v[106:107], v[106:107], v[184:185]
	v_pk_mul_f32 v[102:103], v[102:103], v[180:181]
	v_pk_mul_f32 v[100:101], v[100:101], v[178:179]
	v_pk_mul_f32 v[96:97], v[96:97], v[190:191]
	v_pk_mul_f32 v[92:93], v[92:93], v[186:187]
	v_pk_mul_f32 v[88:89], v[88:89], v[182:183]
	v_pk_mul_f32 v[98:99], v[98:99], v[192:193]
	v_pk_mul_f32 v[94:95], v[94:95], v[188:189]
	v_pk_mul_f32 v[90:91], v[90:91], v[184:185]
	v_pk_mul_f32 v[86:87], v[86:87], v[180:181]
	v_pk_mul_f32 v[84:85], v[84:85], v[178:179]
	v_pk_mul_f32 v[80:81], v[80:81], v[190:191]
	v_pk_mul_f32 v[76:77], v[76:77], v[186:187]
	v_pk_mul_f32 v[72:73], v[72:73], v[182:183]
	v_pk_mul_f32 v[82:83], v[82:83], v[192:193]
	v_pk_mul_f32 v[78:79], v[78:79], v[188:189]
	v_pk_mul_f32 v[74:75], v[74:75], v[184:185]
	v_pk_mul_f32 v[70:71], v[70:71], v[180:181]
	v_pk_mul_f32 v[68:69], v[68:69], v[178:179]
	ds_read_b128 v[178:181], v201 offset:128
	ds_read_b128 v[182:185], v201 offset:160
	ds_read_b128 v[186:189], v201 offset:192
	ds_read_b128 v[190:193], v201 offset:224
	s_waitcnt lgkmcnt(0)
	v_pk_mul_f32 v[54:55], v[54:55], v[180:181]
	v_pk_mul_f32 v[56:57], v[56:57], v[182:183]
	s_nop 0
	v_pk_mul_f32 v[60:61], v[60:61], v[186:187]
	v_pk_mul_f32 v[64:65], v[64:65], v[190:191]
	v_pk_mul_f32 v[66:67], v[66:67], v[192:193]
	v_pk_mul_f32 v[62:63], v[62:63], v[188:189]
	v_pk_mul_f32 v[58:59], v[58:59], v[184:185]
	v_pk_mul_f32 v[52:53], v[52:53], v[178:179]
	v_pk_mul_f32 v[48:49], v[48:49], v[190:191]
	v_pk_mul_f32 v[44:45], v[44:45], v[186:187]
	v_pk_mul_f32 v[40:41], v[40:41], v[182:183]
	v_pk_mul_f32 v[50:51], v[50:51], v[192:193]
	v_pk_mul_f32 v[46:47], v[46:47], v[188:189]
	v_pk_mul_f32 v[42:43], v[42:43], v[184:185]
	v_pk_mul_f32 v[38:39], v[38:39], v[180:181]
	v_pk_mul_f32 v[36:37], v[36:37], v[178:179]
	v_pk_mul_f32 v[32:33], v[32:33], v[190:191]
	v_pk_mul_f32 v[28:29], v[28:29], v[186:187]
	v_pk_mul_f32 v[24:25], v[24:25], v[182:183]
	v_pk_mul_f32 v[34:35], v[34:35], v[192:193]
	v_pk_mul_f32 v[30:31], v[30:31], v[188:189]
	v_pk_mul_f32 v[26:27], v[26:27], v[184:185]
	v_pk_mul_f32 v[22:23], v[22:23], v[180:181]
	v_pk_mul_f32 v[20:21], v[20:21], v[178:179]
	v_pk_mul_f32 v[16:17], v[16:17], v[190:191]
	v_pk_mul_f32 v[12:13], v[12:13], v[186:187]
	v_pk_mul_f32 v[8:9], v[8:9], v[182:183]
	v_pk_mul_f32 v[18:19], v[18:19], v[192:193]
	v_pk_mul_f32 v[14:15], v[14:15], v[188:189]
	v_pk_mul_f32 v[10:11], v[10:11], v[184:185]
	v_pk_mul_f32 v[6:7], v[6:7], v[180:181]
	v_pk_mul_f32 v[4:5], v[4:5], v[178:179]
; #define SBAR() __builtin_amdgcn_sched_barrier(0)
; #define VRD(D0, L) const s16x4 L##0 = tr_read<v_rd_off(D0, 0, 0)>(vb), L##1 = tr_read<v_rd_off(D0, 0, 1)>(vb), L##2 = tr_read<v_rd_off(D0, 1, 0)>(vb), L##3 = tr_read<v_rd_off(D0, 1, 1)>(vb), \
;                          L##4 = tr_read<v_rd_off(D0, 2, 0)>(vb), L##5 = tr_read<v_rd_off(D0, 2, 1)>(vb), L##6 = tr_read<v_rd_off(D0, 3, 0)>(vb), L##7 = tr_read<v_rd_off(D0, 3, 1)>(vb)
; __device__ __forceinline__ void pv_four(f32x16 (&o)[2][4], int vb, bf16x8 pa0, bf16x8 pa1, bf16x8 pa2, bf16x8 pa3, bf16x8 pb0, bf16x8 pb1, bf16x8 pb2, bf16x8 pb3) {
;     ...
;   VRD(0, x); SBAR();
;   VRD(1, y); asm volatile("s_waitcnt lgkmcnt(8)" ::: "memory"); SBAR(); MMA(0, x); SBAR();
;   VRD(2, z); asm volatile("s_waitcnt lgkmcnt(8)" ::: "memory"); SBAR(); MMA(1, y); SBAR();
;   VRD(3, w); asm volatile("s_waitcnt lgkmcnt(8)" ::: "memory"); SBAR(); MMA(2, z); SBAR();
;   asm volatile("s_waitcnt lgkmcnt(0)" ::: "memory"); SBAR(); MMA(3, w);
;     ...
; }
; __device__ __forceinline__ void attn_unit2(const bf16* __restrict__ Qb, const bf16* __restrict__ Kh, const bf16* __restrict__ Vh, bf16* __restrict__ Ob,
;                                            int NT, int lim, int qrow0, const float* lut, char* lds, float* scr) {
;     ...
;         const char* ps = P0 + ((j - 1) & 1) * 16384 + lane * 16;
;         const bf16x8 pa0 = *(const bf16x8*)(ps), pa1 = *(const bf16x8*)(ps + 1024), pa2 = *(const bf16x8*)(ps + 2048), pa3 = *(const bf16x8*)(ps + 3072);
;         const bf16x8 pb0 = *(const bf16x8*)(ps + 4096), pb1 = *(const bf16x8*)(ps + 4096 + 1024), pb2 = *(const bf16x8*)(ps + 4096 + 2048), pb3 = *(const bf16x8*)(ps + 4096 + 3072);
;         const int vb = vrb + ((j - 1) & 1) * 32768 + ch * 16384;
;         pv_four(o, vb, pa0, pa1, pa2, pa3, pb0, pb1, pb2, pb3);
;       }
;       asm volatile("s_waitcnt vmcnt(0)" ::: "memory");
;       __syncthreads();
.LBB0_436:
	v_lshl_add_u32 v201, s14, 14, v175
	ds_read_b128 v[178:181], v201
	ds_read_b128 v[182:185], v201 offset:1024
	ds_read_b128 v[186:189], v201 offset:2048
	ds_read_b128 v[190:193], v201 offset:3072
	ds_read_b128 v[194:197], v201 offset:4096
	ds_read_b128 v[208:211], v201 offset:5120
	ds_read_b128 v[212:215], v201 offset:6144
	ds_read_b128 v[216:219], v201 offset:7168
	v_lshl_add_u32 v207, s14, 15, v176
	ds_read_b64_tr_b16 v[220:221], v207 offset:0
	ds_read_b64_tr_b16 v[222:223], v207 offset:0x800
	ds_read_b64_tr_b16 v[224:225], v207 offset:0x1000
	ds_read_b64_tr_b16 v[226:227], v207 offset:0x1800
	ds_read_b64_tr_b16 v[228:229], v207 offset:0x2000
	ds_read_b64_tr_b16 v[230:231], v207 offset:0x2800
	ds_read_b64_tr_b16 v[232:233], v207 offset:0x3000
	ds_read_b64_tr_b16 v[234:235], v207 offset:0x3800
	ds_read_b64_tr_b16 v[236:237], v207 offset:0x200
	ds_read_b64_tr_b16 v[238:239], v207 offset:0xa00
	ds_read_b64_tr_b16 v[240:241], v207 offset:0x1200
	ds_read_b64_tr_b16 v[242:243], v207 offset:0x1a00
	ds_read_b64_tr_b16 v[244:245], v207 offset:0x2200
	s_add_i32 m0, s23, 0xc000
	ds_read_b64_tr_b16 v[246:247], v207 offset:0x2a00
	global_load_lds_dwordx4 v[156:157], off
	s_add_i32 m0, s23, 0xc400
	ds_read_b64_tr_b16 v[248:249], v207 offset:0x3200
	global_load_lds_dwordx4 v[158:159], off
	s_add_i32 m0, s23, 0xc800
	ds_read_b64_tr_b16 v[250:251], v207 offset:0x3a00
	global_load_lds_dwordx4 v[164:165], off
	s_add_i32 m0, s23, 0xcc00
	s_nop 0
	s_nop 0
	global_load_lds_dwordx4 v[252:253], off
	s_waitcnt lgkmcnt(8)
	s_waitcnt lgkmcnt(0)
	v_mfma_f32_32x32x16_bf16 v[116:131], v[178:181], v[220:223], v[116:131]
	v_mfma_f32_32x32x16_bf16 v[52:67], v[194:197], v[220:223], v[52:67]
	v_mfma_f32_32x32x16_bf16 v[116:131], v[182:185], v[224:227], v[116:131]
	v_mfma_f32_32x32x16_bf16 v[52:67], v[208:211], v[224:227], v[52:67]
	v_mfma_f32_32x32x16_bf16 v[116:131], v[186:189], v[228:231], v[116:131]
	v_mfma_f32_32x32x16_bf16 v[52:67], v[212:215], v[228:231], v[52:67]
	v_mfma_f32_32x32x16_bf16 v[116:131], v[190:193], v[232:235], v[116:131]
	v_mfma_f32_32x32x16_bf16 v[52:67], v[216:219], v[232:235], v[52:67]
	ds_read_b64_tr_b16 v[220:221], v207 offset:0x400
	ds_read_b64_tr_b16 v[222:223], v207 offset:0xc00
	ds_read_b64_tr_b16 v[224:225], v207 offset:0x1400
	ds_read_b64_tr_b16 v[226:227], v207 offset:0x1c00
	ds_read_b64_tr_b16 v[228:229], v207 offset:0x2400
	ds_read_b64_tr_b16 v[230:231], v207 offset:0x2c00
	ds_read_b64_tr_b16 v[232:233], v207 offset:0x3400
	ds_read_b64_tr_b16 v[234:235], v207 offset:0x3c00
	s_waitcnt lgkmcnt(8)
	v_mfma_f32_32x32x16_bf16 v[100:115], v[178:181], v[236:239], v[100:115]
	v_mfma_f32_32x32x16_bf16 v[36:51], v[194:197], v[236:239], v[36:51]
	v_mfma_f32_32x32x16_bf16 v[100:115], v[182:185], v[240:243], v[100:115]
	v_mfma_f32_32x32x16_bf16 v[36:51], v[208:211], v[240:243], v[36:51]
	v_mfma_f32_32x32x16_bf16 v[100:115], v[186:189], v[244:247], v[100:115]
	s_nop 0
	v_mfma_f32_32x32x16_bf16 v[36:51], v[212:215], v[244:247], v[36:51]
	v_mfma_f32_32x32x16_bf16 v[100:115], v[190:193], v[248:251], v[100:115]
	v_mfma_f32_32x32x16_bf16 v[36:51], v[216:219], v[248:251], v[36:51]
	ds_read_b64_tr_b16 v[236:237], v207 offset:0x600
	ds_read_b64_tr_b16 v[238:239], v207 offset:0xe00
	ds_read_b64_tr_b16 v[240:241], v207 offset:0x1600
	ds_read_b64_tr_b16 v[242:243], v207 offset:0x1e00
	ds_read_b64_tr_b16 v[244:245], v207 offset:0x2600
	ds_read_b64_tr_b16 v[246:247], v207 offset:0x2e00
	ds_read_b64_tr_b16 v[248:249], v207 offset:0x3600
	ds_read_b64_tr_b16 v[250:251], v207 offset:0x3e00
	s_waitcnt lgkmcnt(8)
	v_mfma_f32_32x32x16_bf16 v[84:99], v[178:181], v[220:223], v[84:99]
	v_mfma_f32_32x32x16_bf16 v[20:35], v[194:197], v[220:223], v[20:35]
	v_mfma_f32_32x32x16_bf16 v[84:99], v[182:185], v[224:227], v[84:99]
	v_mfma_f32_32x32x16_bf16 v[20:35], v[208:211], v[224:227], v[20:35]
	s_nop 0
	v_mfma_f32_32x32x16_bf16 v[84:99], v[186:189], v[228:231], v[84:99]
	v_mfma_f32_32x32x16_bf16 v[20:35], v[212:215], v[228:231], v[20:35]
	v_mfma_f32_32x32x16_bf16 v[84:99], v[190:193], v[232:235], v[84:99]
	v_mfma_f32_32x32x16_bf16 v[20:35], v[216:219], v[232:235], v[20:35]
	s_waitcnt lgkmcnt(0)
	v_mfma_f32_32x32x16_bf16 v[68:83], v[178:181], v[236:239], v[68:83]
	s_add_i32 s9, s9, 0x8000
	s_waitcnt vmcnt(0)
	s_add_u32 s36, s36, 0x40000
	s_addc_u32 s37, s37, 0
	s_add_i32 s14, s10, 1
	s_addk_i32 s7, 0x4000
	s_cmp_eq_u32 s8, s36
	v_mfma_f32_32x32x16_bf16 v[4:19], v[194:197], v[236:239], v[4:19]
	s_waitcnt vmcnt(0)
	s_barrier
	v_mfma_f32_32x32x16_bf16 v[68:83], v[182:185], v[240:243], v[68:83]
	v_mfma_f32_32x32x16_bf16 v[4:19], v[208:211], v[240:243], v[4:19]
	v_mfma_f32_32x32x16_bf16 v[68:83], v[186:189], v[244:247], v[68:83]
	v_mfma_f32_32x32x16_bf16 v[4:19], v[212:215], v[244:247], v[4:19]
	v_mfma_f32_32x32x16_bf16 v[68:83], v[190:193], v[248:251], v[68:83]
	v_mfma_f32_32x32x16_bf16 v[4:19], v[216:219], v[248:251], v[4:19]
	s_cbranch_scc1 .LBB0_439
	s_mov_b32 s10, s14
	s_cmp_lt_u32 s10, s5
	s_cselect_b64 s[38:39], -1, 0
	s_cmp_ge_u32 s10, s5
	s_cbranch_scc0 .LBB0_432
	s_branch .LBB0_433
